# mLSTM phase: static s_setprio 1 for wave 7 (the wave that carries the serial gate scan each chunk and arrives last at the chunk barrier) for the duration of the unit
# speedup vs baseline: 1.0195x; 1.0195x over previous
; #define LAS __attribute__((address_space(3)))
; __device__ __forceinline__ int opaque_tid() { int t = threadIdx.x; asm volatile("" : "+v"(t)); return t; }
; __device__ __forceinline__ const float* ka_in(KArg k, int i) { return *(const float* const __attribute__((address_space(4)))*)(k + 8 * i); }
; __device__ __forceinline__ unsigned char* ka_ws(KArg k) { return *(unsigned char* const __attribute__((address_space(4)))*)(k + 216); }
; __device__ __forceinline__ void mlstm_unit(KArg P, int L, int b, int h, int vs, LAS unsigned char* lds) {
;     const int tid = opaque_tid(), lane = tid & 63, w = __builtin_amdgcn_readfirstlane(tid >> 6), c = lane & 15, g = lane >> 4;
;     bf16* Z = (bf16*)(ka_ws(P) + WS_Z); const float* gif = (const float*)(ka_ws(P) + WS_GIF);
;     LAS float* FL = (LAS float*)(lds + ML_FL);
;     const int cgp = lane, isk = cgp >> 5;
;     const int zcol = (isk ? 1024 : 0) + h * 256 + (cgp & 31) * 8;
;     const float bi = ka_in(P, 10)[L * 4 + h], bfg = ka_in(P, 11)[L * 4 + h];
;     const size_t rowbase = (size_t)b * SEQ;
;     for (int i = tid; i < 32 * 264 / 2; i += 512) ((LAS unsigned*)(lds + ML_CB))[i] = 0u;
;     if (tid < 128) ((LAS unsigned*)(lds + ML_NB))[tid] = 0u;
;     ...
;         __syncthreads();
;         if (ch + 1 < 64) stage_kt_v(FL + ((ch + 1) & 1) * FL_GSZ);
;     }
;     __syncthreads();
.LBB0_499:
	v_readlane_b32 s2, v254, 40
	s_add_i32 s51, s51, s2
	s_cmpk_gt_i32 s51, 0xff
	s_waitcnt lgkmcnt(0)
	s_barrier
	s_setprio 0
	s_cbranch_scc1 .LBB0_561
.LBB0_500:
	v_readlane_b32 s2, v254, 38
	v_mov_b32_e32 v42, v155
	v_readlane_b32 s3, v254, 39
	s_load_dwordx4 s[8:11], s[2:3], 0x50
	s_and_b32 s34, s51, 3
	s_or_b32 s2, s34, s50
	s_ashr_i32 s3, s2, 31
	s_lshl_b64 s[2:3], s[2:3], 2
	s_waitcnt lgkmcnt(0)
	s_add_u32 s6, s8, s2
	s_addc_u32 s7, s9, s3
	s_add_u32 s2, s10, s2
	s_addc_u32 s3, s11, s3
	global_load_dword v94, v1, s[6:7]
	global_load_dword v95, v1, s[2:3]
	s_movk_i32 s2, 0x1080
	v_readfirstlane_b32 s35, v42
	v_cmp_gt_i32_e32 vcc, s2, v42
	s_lshr_b32 s4, s35, 6
	s_cmp_eq_u32 s4, 7
	s_cbranch_scc0 .Lml_noprio
	s_setprio 1
.Lml_noprio:
	s_and_saveexec_b64 s[2:3], vcc
	s_cbranch_execz .LBB0_503
	v_readlane_b32 s4, v254, 17
	v_add_u32_e32 v0, 0xfffffe00, v42
	s_mov_b64 s[6:7], 0
	s_waitcnt vmcnt(0)
	v_lshl_add_u32 v2, v42, 2, s4
